# v11 plus write-through (sc1) stores in the input-projection epilogues
# baseline (speedup 1.0000x reference)
; __device__ __forceinline__ float bf_lo(unsigned w) { return __uint_as_float(w << 16); }
;     __device__ __forceinline__ void operator()(const f32x4 (&acc)[2][2][4][2], const pg8::Unit& u, int wr, int wc, int fr_, int fq_) const {
;     ...
;             const int row0 = u.pm * 256 + wr * 64 + fr, col0 = colt + wc * 32 + 8 * fq;
; #pragma unroll
;             for (int ai = 0; ai < 2; ++ai)
; #pragma unroll
;                 for (int m = 0; m < 4; ++m) { const size_t roff = (size_t)(row0 + ai * 128 + m * 16) * ld + col0;
; #pragma unroll
;                     for (int bj = 0; bj < 2; ++bj) { f32x4 v0 = acc[ai][bj][m][0], v1 = acc[ai][bj][m][1]; const size_t off = roff + bj * 128;
;                         float v[8] = {v0[0], v0[1], v0[2], v0[3], v1[0], v1[1], v1[2], v1[3]};
;                         if constexpr (MODE == EPI_INPROJ) {
; #pragma unroll
;                             for (int i = 0; i < 8; ++i) v[i] *= sc;
;                         }
;                         if constexpr (MODE == EPI_GLU) {
;                             const u32x4 yg = *(const u32x4*)(X1 + off); const u32x4 zs = *(const u32x4*)(base + off);
; #pragma unroll
;                             for (int i = 0; i < 4; ++i) { v[2 * i] = bf_lo(yg[i]) * sigm(v[2 * i] * sc_all) * silu(bf_lo(zs[i])); v[2 * i + 1] = bf_hi(yg[i]) * sigm(v[2 * i + 1] * sc_all) * silu(bf_hi(zs[i])); }
;                         }
;                         if constexpr (MODE == EPI_MRG_A) {
;                             const u32x4 ga = *(const u32x4*)(base + off);
; #pragma unroll
;                             for (int i = 0; i < 4; ++i) { v[2 * i] *= sigm(bf_lo(ga[i])); v[2 * i + 1] *= sigm(bf_hi(ga[i])); }
;                         }
;                         if constexpr (MODE == EPI_MRG_B) {
;                             const u32x4 ga = *(const u32x4*)(base + off); const u32x4 gs = *(const u32x4*)(X1 + off);
; #pragma unroll
;                             for (int i = 0; i < 4; ++i) { v[2 * i] = bf_lo(ga[i]) + sigm(bf_lo(gs[i])) * v[2 * i]; v[2 * i + 1] = bf_hi(ga[i]) + sigm(bf_hi(gs[i])) * v[2 * i + 1]; }
;                         }
;                         if constexpr (MODE == EPI_OUT_A) {
;                             const f32x4 r0 = *(const f32x4*)(res + off), r1 = *(const f32x4*)(res + off + 4); const u32x4 pl = *(const u32x4*)(X1 + off);
;                             f32x4 o0, o1;
.LBB0_132:
	s_lshl_b32 s10, s20, 8
	s_add_i32 s10, s10, s63
	v_and_or_b32 v3, v0, 15, s10
	v_lshrrev_b32_e32 v0, 1, v0
	v_and_or_b32 v0, v0, 24, s4
	v_or_b32_e32 v162, s80, v0
	v_lshl_add_u64 v[0:1], v[162:163], 1, s[22:23]
	v_mad_i64_i32 v[4:5], s[20:21], s38, v3, 0
	v_lshl_add_u64 v[8:9], v[4:5], 1, v[0:1]
	v_mul_f32_e32 v4, v156, v2
	v_mul_f32_e32 v5, v157, v2
	v_mul_f32_e32 v6, v158, v2
	v_mul_f32_e32 v7, v159, v2
	v_cvt_pk_bf16_f32 v4, v4, v5
	v_mul_f32_e32 v10, v152, v2
	v_mul_f32_e32 v11, v153, v2
	v_mul_f32_e32 v12, v154, v2
	v_mul_f32_e32 v13, v155, v2
	v_cvt_pk_bf16_f32 v5, v6, v7
	v_cvt_pk_bf16_f32 v6, v10, v11
	v_cvt_pk_bf16_f32 v7, v12, v13
	flat_store_dwordx4 v[8:9], v[4:7] sc1
	v_mul_f32_e32 v10, v136, v2
	v_mul_f32_e32 v11, v137, v2
	v_mul_f32_e32 v4, v144, v2
	v_mul_f32_e32 v5, v145, v2
	v_mul_f32_e32 v6, v146, v2
	v_mul_f32_e32 v7, v147, v2
	v_cvt_pk_bf16_f32 v4, v4, v5
	v_mul_f32_e32 v12, v138, v2
	v_mul_f32_e32 v13, v139, v2
	v_cvt_pk_bf16_f32 v5, v6, v7
	v_cvt_pk_bf16_f32 v6, v10, v11
	v_cvt_pk_bf16_f32 v7, v12, v13
	flat_store_dwordx4 v[8:9], v[4:7] offset:256 sc1
	v_mul_f32_e32 v10, v140, v2
	v_mul_f32_e32 v11, v141, v2
	v_or_b32_e32 v4, 16, v3
	v_mad_i64_i32 v[4:5], s[20:21], s38, v4, 0
	v_lshl_add_u64 v[8:9], v[4:5], 1, v[0:1]
	v_mul_f32_e32 v4, v148, v2
	v_mul_f32_e32 v5, v149, v2
	v_mul_f32_e32 v6, v150, v2
	v_mul_f32_e32 v7, v151, v2
	v_cvt_pk_bf16_f32 v4, v4, v5
	v_mul_f32_e32 v12, v142, v2
	v_mul_f32_e32 v13, v143, v2
	v_cvt_pk_bf16_f32 v5, v6, v7
	v_cvt_pk_bf16_f32 v6, v10, v11
	v_cvt_pk_bf16_f32 v7, v12, v13
	flat_store_dwordx4 v[8:9], v[4:7] sc1
	v_mul_f32_e32 v10, v120, v2
	v_mul_f32_e32 v11, v121, v2
	v_mul_f32_e32 v4, v128, v2
	v_mul_f32_e32 v5, v129, v2
	v_mul_f32_e32 v6, v130, v2
	v_mul_f32_e32 v7, v131, v2
	v_cvt_pk_bf16_f32 v4, v4, v5
	v_mul_f32_e32 v12, v122, v2
	v_mul_f32_e32 v13, v123, v2
	v_cvt_pk_bf16_f32 v5, v6, v7
	v_cvt_pk_bf16_f32 v6, v10, v11
	v_cvt_pk_bf16_f32 v7, v12, v13
	flat_store_dwordx4 v[8:9], v[4:7] offset:256 sc1
	v_mul_f32_e32 v10, v124, v2
	v_mul_f32_e32 v11, v125, v2
	v_or_b32_e32 v4, 32, v3
	v_mad_i64_i32 v[4:5], s[20:21], s38, v4, 0
	v_lshl_add_u64 v[8:9], v[4:5], 1, v[0:1]
	v_mul_f32_e32 v4, v132, v2
	v_mul_f32_e32 v5, v133, v2
	v_mul_f32_e32 v6, v134, v2
	v_mul_f32_e32 v7, v135, v2
	v_cvt_pk_bf16_f32 v4, v4, v5
	v_mul_f32_e32 v12, v126, v2
	v_mul_f32_e32 v13, v127, v2
	v_cvt_pk_bf16_f32 v5, v6, v7
	v_cvt_pk_bf16_f32 v6, v10, v11
	v_cvt_pk_bf16_f32 v7, v12, v13
	flat_store_dwordx4 v[8:9], v[4:7] sc1
	v_mul_f32_e32 v10, v104, v2
	v_mul_f32_e32 v11, v105, v2
	v_mul_f32_e32 v4, v112, v2
	v_mul_f32_e32 v5, v113, v2
	v_mul_f32_e32 v6, v114, v2
	v_mul_f32_e32 v7, v115, v2
	v_cvt_pk_bf16_f32 v4, v4, v5
	v_mul_f32_e32 v12, v106, v2
	v_mul_f32_e32 v13, v107, v2
	v_cvt_pk_bf16_f32 v5, v6, v7
	v_cvt_pk_bf16_f32 v6, v10, v11
	v_cvt_pk_bf16_f32 v7, v12, v13
	flat_store_dwordx4 v[8:9], v[4:7] offset:256 sc1
	v_mul_f32_e32 v10, v108, v2
	v_mul_f32_e32 v11, v109, v2
	v_or_b32_e32 v4, 48, v3
	v_mad_i64_i32 v[4:5], s[20:21], s38, v4, 0
	v_lshl_add_u64 v[8:9], v[4:5], 1, v[0:1]
	v_mul_f32_e32 v4, v116, v2
	v_mul_f32_e32 v5, v117, v2
	v_mul_f32_e32 v6, v118, v2
	v_mul_f32_e32 v7, v119, v2
	v_cvt_pk_bf16_f32 v4, v4, v5
	v_mul_f32_e32 v12, v110, v2
	v_mul_f32_e32 v13, v111, v2
	v_cvt_pk_bf16_f32 v5, v6, v7
	v_cvt_pk_bf16_f32 v6, v10, v11
	v_cvt_pk_bf16_f32 v7, v12, v13
	flat_store_dwordx4 v[8:9], v[4:7] sc1
	v_mul_f32_e32 v10, v96, v2
	v_mul_f32_e32 v11, v97, v2
	v_mul_f32_e32 v4, v100, v2
	v_mul_f32_e32 v5, v101, v2
	v_mul_f32_e32 v6, v102, v2
	v_mul_f32_e32 v7, v103, v2
	v_cvt_pk_bf16_f32 v4, v4, v5
	v_mul_f32_e32 v12, v98, v2
	v_mul_f32_e32 v13, v99, v2
	v_cvt_pk_bf16_f32 v5, v6, v7
	v_cvt_pk_bf16_f32 v6, v10, v11
	v_cvt_pk_bf16_f32 v7, v12, v13
; __device__ __forceinline__ float bf_lo(unsigned w) { return __uint_as_float(w << 16); }
;     __device__ __forceinline__ void operator()(const f32x4 (&acc)[2][2][4][2], const pg8::Unit& u, int wr, int wc, int fr_, int fq_) const {
;     ...
;             const int row0 = u.pm * 256 + wr * 64 + fr, col0 = colt + wc * 32 + 8 * fq;
; #pragma unroll
;             for (int ai = 0; ai < 2; ++ai)
; #pragma unroll
;                 for (int m = 0; m < 4; ++m) { const size_t roff = (size_t)(row0 + ai * 128 + m * 16) * ld + col0;
; #pragma unroll
;                     for (int bj = 0; bj < 2; ++bj) { f32x4 v0 = acc[ai][bj][m][0], v1 = acc[ai][bj][m][1]; const size_t off = roff + bj * 128;
;                         float v[8] = {v0[0], v0[1], v0[2], v0[3], v1[0], v1[1], v1[2], v1[3]};
;                         if constexpr (MODE == EPI_INPROJ) {
; #pragma unroll
;                             for (int i = 0; i < 8; ++i) v[i] *= sc;
;                         }
;                         if constexpr (MODE == EPI_GLU) {
;                             const u32x4 yg = *(const u32x4*)(X1 + off); const u32x4 zs = *(const u32x4*)(base + off);
; #pragma unroll
;                             for (int i = 0; i < 4; ++i) { v[2 * i] = bf_lo(yg[i]) * sigm(v[2 * i] * sc_all) * silu(bf_lo(zs[i])); v[2 * i + 1] = bf_hi(yg[i]) * sigm(v[2 * i + 1] * sc_all) * silu(bf_hi(zs[i])); }
;                         }
;                         if constexpr (MODE == EPI_MRG_A) {
;                             const u32x4 ga = *(const u32x4*)(base + off);
; #pragma unroll
;                             for (int i = 0; i < 4; ++i) { v[2 * i] *= sigm(bf_lo(ga[i])); v[2 * i + 1] *= sigm(bf_hi(ga[i])); }
;                         }
;                         if constexpr (MODE == EPI_MRG_B) {
;                             const u32x4 ga = *(const u32x4*)(base + off); const u32x4 gs = *(const u32x4*)(X1 + off);
; #pragma unroll
;                             for (int i = 0; i < 4; ++i) { v[2 * i] = bf_lo(ga[i]) + sigm(bf_lo(gs[i])) * v[2 * i]; v[2 * i + 1] = bf_hi(ga[i]) + sigm(bf_hi(gs[i])) * v[2 * i + 1]; }
;                         }
;                         if constexpr (MODE == EPI_OUT_A) {
;                             const f32x4 r0 = *(const f32x4*)(res + off), r1 = *(const f32x4*)(res + off + 4); const u32x4 pl = *(const u32x4*)(X1 + off);
;                             f32x4 o0, o1;
	flat_store_dwordx4 v[8:9], v[4:7] offset:256 sc1
	v_mul_f32_e32 v10, v88, v2
	v_mul_f32_e32 v11, v89, v2
	v_add_u32_e32 v4, 0x80, v3
	v_mad_i64_i32 v[4:5], s[20:21], s38, v4, 0
	v_lshl_add_u64 v[8:9], v[4:5], 1, v[0:1]
	v_mul_f32_e32 v4, v92, v2
	v_mul_f32_e32 v5, v93, v2
	v_mul_f32_e32 v6, v94, v2
	v_mul_f32_e32 v7, v95, v2
	v_cvt_pk_bf16_f32 v4, v4, v5
	v_mul_f32_e32 v12, v90, v2
	v_mul_f32_e32 v13, v91, v2
	v_cvt_pk_bf16_f32 v5, v6, v7
	v_cvt_pk_bf16_f32 v6, v10, v11
	v_cvt_pk_bf16_f32 v7, v12, v13
	flat_store_dwordx4 v[8:9], v[4:7] sc1
	v_mul_f32_e32 v10, v72, v2
	v_mul_f32_e32 v11, v73, v2
	v_mul_f32_e32 v4, v80, v2
	v_mul_f32_e32 v5, v81, v2
	v_mul_f32_e32 v6, v82, v2
	v_mul_f32_e32 v7, v83, v2
	v_cvt_pk_bf16_f32 v4, v4, v5
	v_mul_f32_e32 v12, v74, v2
	v_mul_f32_e32 v13, v75, v2
	v_cvt_pk_bf16_f32 v5, v6, v7
	v_cvt_pk_bf16_f32 v6, v10, v11
	v_cvt_pk_bf16_f32 v7, v12, v13
	flat_store_dwordx4 v[8:9], v[4:7] offset:256 sc1
	v_mul_f32_e32 v10, v76, v2
	v_mul_f32_e32 v11, v77, v2
	v_add_u32_e32 v4, 0x90, v3
	v_mad_i64_i32 v[4:5], s[20:21], s38, v4, 0
	v_lshl_add_u64 v[8:9], v[4:5], 1, v[0:1]
	v_mul_f32_e32 v4, v84, v2
	v_mul_f32_e32 v5, v85, v2
	v_mul_f32_e32 v6, v86, v2
	v_mul_f32_e32 v7, v87, v2
	v_cvt_pk_bf16_f32 v4, v4, v5
	v_mul_f32_e32 v12, v78, v2
	v_mul_f32_e32 v13, v79, v2
	v_cvt_pk_bf16_f32 v5, v6, v7
	v_cvt_pk_bf16_f32 v6, v10, v11
	v_cvt_pk_bf16_f32 v7, v12, v13
	flat_store_dwordx4 v[8:9], v[4:7] sc1
	v_mul_f32_e32 v10, v56, v2
	v_mul_f32_e32 v11, v57, v2
	v_mul_f32_e32 v4, v64, v2
	v_mul_f32_e32 v5, v65, v2
	v_mul_f32_e32 v6, v66, v2
	v_mul_f32_e32 v7, v67, v2
	v_cvt_pk_bf16_f32 v4, v4, v5
	v_mul_f32_e32 v12, v58, v2
	v_mul_f32_e32 v13, v59, v2
	v_cvt_pk_bf16_f32 v5, v6, v7
	v_cvt_pk_bf16_f32 v6, v10, v11
	v_cvt_pk_bf16_f32 v7, v12, v13
	flat_store_dwordx4 v[8:9], v[4:7] offset:256 sc1
	v_mul_f32_e32 v10, v60, v2
	v_mul_f32_e32 v11, v61, v2
	v_add_u32_e32 v4, 0xa0, v3
	v_mad_i64_i32 v[4:5], s[20:21], s38, v4, 0
	v_lshl_add_u64 v[8:9], v[4:5], 1, v[0:1]
	v_mul_f32_e32 v4, v68, v2
	v_mul_f32_e32 v5, v69, v2
	v_mul_f32_e32 v6, v70, v2
	v_mul_f32_e32 v7, v71, v2
	v_cvt_pk_bf16_f32 v4, v4, v5
	v_cvt_pk_bf16_f32 v5, v6, v7
	v_mul_f32_e32 v12, v62, v2
	v_mul_f32_e32 v13, v63, v2
	v_cvt_pk_bf16_f32 v6, v10, v11
	v_cvt_pk_bf16_f32 v7, v12, v13
	flat_store_dwordx4 v[8:9], v[4:7] sc1
	v_add_u32_e32 v3, 0xb0, v3
	v_mul_f32_e32 v10, v40, v2
	v_mul_f32_e32 v4, v48, v2
	v_mul_f32_e32 v5, v49, v2
	v_mul_f32_e32 v6, v50, v2
	v_mul_f32_e32 v7, v51, v2
	v_cvt_pk_bf16_f32 v4, v4, v5
	v_cvt_pk_bf16_f32 v5, v6, v7
	v_mul_f32_e32 v11, v41, v2
	v_mul_f32_e32 v12, v42, v2
	v_mul_f32_e32 v13, v43, v2
	v_cvt_pk_bf16_f32 v6, v10, v11
	v_cvt_pk_bf16_f32 v7, v12, v13
	flat_store_dwordx4 v[8:9], v[4:7] offset:256 sc1
	v_mul_f32_e32 v10, v46, v2
	v_mul_f32_e32 v11, v47, v2
	v_mad_i64_i32 v[4:5], s[20:21], s38, v3, 0
	v_lshl_add_u64 v[8:9], v[4:5], 1, v[0:1]
	v_mul_f32_e32 v0, v52, v2
	v_mul_f32_e32 v1, v53, v2
	v_mul_f32_e32 v3, v54, v2
	v_mul_f32_e32 v5, v55, v2
	v_mul_f32_e32 v6, v44, v2
	v_mul_f32_e32 v7, v45, v2
	v_cvt_pk_bf16_f32 v4, v0, v1
	v_cvt_pk_bf16_f32 v5, v3, v5
	v_cvt_pk_bf16_f32 v6, v6, v7
	v_cvt_pk_bf16_f32 v7, v10, v11
	v_mul_f32_e32 v0, v36, v2
	v_mul_f32_e32 v1, v37, v2
	v_mul_f32_e32 v3, v38, v2
	s_andn2_b64 vcc, exec, s[36:37]
	s_mov_b64 s[20:21], -1
	flat_store_dwordx4 v[8:9], v[4:7] sc1
	v_mul_f32_e32 v10, v35, v2
	v_cvt_pk_bf16_f32 v0, v0, v1
	s_nop 0
	v_mul_f32_e32 v4, v39, v2
	v_mul_f32_e32 v5, v32, v2
	v_mul_f32_e32 v6, v33, v2
	v_mul_f32_e32 v7, v34, v2
	v_cvt_pk_bf16_f32 v1, v3, v4
	v_cvt_pk_bf16_f32 v2, v5, v6
	v_cvt_pk_bf16_f32 v3, v7, v10
	flat_store_dwordx4 v[8:9], v[0:3] offset:256 sc1
	s_cbranch_vccnz .LBB0_115
	s_andn2_b64 vcc, exec, s[6:7]
	s_cbranch_vccnz .LBB0_114
	s_barrier
	s_branch .LBB0_114

; __device__ __forceinline__ float bf_lo(unsigned w) { return __uint_as_float(w << 16); }
;     __device__ __forceinline__ void operator()(const f32x4 (&acc)[2][2][4][2], const pg8::Unit& u, int wr, int wc, int fr_, int fq_) const {
;     ...
;             const int row0 = u.pm * 256 + wr * 64 + fr, col0 = colt + wc * 32 + 8 * fq;
; #pragma unroll
;             for (int ai = 0; ai < 2; ++ai)
; #pragma unroll
;                 for (int m = 0; m < 4; ++m) { const size_t roff = (size_t)(row0 + ai * 128 + m * 16) * ld + col0;
; #pragma unroll
;                     for (int bj = 0; bj < 2; ++bj) { f32x4 v0 = acc[ai][bj][m][0], v1 = acc[ai][bj][m][1]; const size_t off = roff + bj * 128;
;                         float v[8] = {v0[0], v0[1], v0[2], v0[3], v1[0], v1[1], v1[2], v1[3]};
;                         if constexpr (MODE == EPI_INPROJ) {
; #pragma unroll
;                             for (int i = 0; i < 8; ++i) v[i] *= sc;
;                         }
;                         if constexpr (MODE == EPI_GLU) {
;                             const u32x4 yg = *(const u32x4*)(X1 + off); const u32x4 zs = *(const u32x4*)(base + off);
; #pragma unroll
;                             for (int i = 0; i < 4; ++i) { v[2 * i] = bf_lo(yg[i]) * sigm(v[2 * i] * sc_all) * silu(bf_lo(zs[i])); v[2 * i + 1] = bf_hi(yg[i]) * sigm(v[2 * i + 1] * sc_all) * silu(bf_hi(zs[i])); }
;                         }
;                         if constexpr (MODE == EPI_MRG_A) {
;                             const u32x4 ga = *(const u32x4*)(base + off);
; #pragma unroll
;                             for (int i = 0; i < 4; ++i) { v[2 * i] *= sigm(bf_lo(ga[i])); v[2 * i + 1] *= sigm(bf_hi(ga[i])); }
;                         }
;                         if constexpr (MODE == EPI_MRG_B) {
;                             const u32x4 ga = *(const u32x4*)(base + off); const u32x4 gs = *(const u32x4*)(X1 + off);
; #pragma unroll
;                             for (int i = 0; i < 4; ++i) { v[2 * i] = bf_lo(ga[i]) + sigm(bf_lo(gs[i])) * v[2 * i]; v[2 * i + 1] = bf_hi(ga[i]) + sigm(bf_hi(gs[i])) * v[2 * i + 1]; }
;                         }
;                         if constexpr (MODE == EPI_OUT_A) {
;                             const f32x4 r0 = *(const f32x4*)(res + off), r1 = *(const f32x4*)(res + off + 4); const u32x4 pl = *(const u32x4*)(X1 + off);
;                             f32x4 o0, o1;
.LBB0_169:
	s_lshl_b32 s4, s18, 8
	s_add_i32 s4, s4, s59
	v_and_or_b32 v145, v140, 15, s4
	v_lshrrev_b32_e32 v140, 1, v140
	v_and_or_b32 v140, v140, 24, s3
	v_or_b32_e32 v162, s60, v140
	v_lshl_add_u64 v[140:141], v[162:163], 1, s[22:23]
	v_mad_i64_i32 v[146:147], s[18:19], s20, v145, 0
	v_lshl_add_u64 v[146:147], v[146:147], 1, v[140:141]
	v_mul_f32_e32 v124, v124, v144
	v_mul_f32_e32 v125, v125, v144
	v_mul_f32_e32 v148, v120, v144
	v_mul_f32_e32 v123, v123, v144
	v_cvt_pk_bf16_f32 v120, v124, v125
	v_mul_f32_e32 v126, v126, v144
	v_mul_f32_e32 v127, v127, v144
	v_mul_f32_e32 v149, v121, v144
	v_mul_f32_e32 v150, v122, v144
	v_cvt_pk_bf16_f32 v121, v126, v127
	v_cvt_pk_bf16_f32 v122, v148, v149
	v_cvt_pk_bf16_f32 v123, v150, v123
	flat_store_dwordx4 v[146:147], v[120:123] sc1
	v_mul_f32_e32 v112, v112, v144
	v_mul_f32_e32 v113, v113, v144
	v_mul_f32_e32 v120, v104, v144
	v_mul_f32_e32 v107, v107, v144
	v_cvt_pk_bf16_f32 v104, v112, v113
	v_mul_f32_e32 v114, v114, v144
	v_mul_f32_e32 v115, v115, v144
	v_mul_f32_e32 v121, v105, v144
	v_mul_f32_e32 v122, v106, v144
	v_cvt_pk_bf16_f32 v105, v114, v115
	v_cvt_pk_bf16_f32 v106, v120, v121
	v_cvt_pk_bf16_f32 v107, v122, v107
	flat_store_dwordx4 v[146:147], v[104:107] offset:256 sc1
	v_mul_f32_e32 v108, v108, v144
	v_mul_f32_e32 v109, v109, v144
	v_or_b32_e32 v104, 16, v145
	v_mad_i64_i32 v[104:105], s[18:19], s20, v104, 0
	v_lshl_add_u64 v[112:113], v[104:105], 1, v[140:141]
	v_mul_f32_e32 v104, v116, v144
	v_mul_f32_e32 v105, v117, v144
	v_mul_f32_e32 v106, v118, v144
	v_mul_f32_e32 v107, v119, v144
	v_cvt_pk_bf16_f32 v104, v104, v105
	v_mul_f32_e32 v110, v110, v144
	v_mul_f32_e32 v111, v111, v144
	v_cvt_pk_bf16_f32 v105, v106, v107
	v_cvt_pk_bf16_f32 v106, v108, v109
	v_cvt_pk_bf16_f32 v107, v110, v111
	flat_store_dwordx4 v[112:113], v[104:107] sc1
	v_mul_f32_e32 v96, v96, v144
	v_mul_f32_e32 v97, v97, v144
	v_mul_f32_e32 v104, v88, v144
	v_mul_f32_e32 v91, v91, v144
	v_cvt_pk_bf16_f32 v88, v96, v97
	v_mul_f32_e32 v98, v98, v144
	v_mul_f32_e32 v99, v99, v144
	v_mul_f32_e32 v105, v89, v144
	v_mul_f32_e32 v106, v90, v144
	v_cvt_pk_bf16_f32 v89, v98, v99
	v_cvt_pk_bf16_f32 v90, v104, v105
	v_cvt_pk_bf16_f32 v91, v106, v91
	flat_store_dwordx4 v[112:113], v[88:91] offset:256 sc1
	v_mul_f32_e32 v92, v92, v144
	v_mul_f32_e32 v93, v93, v144
	v_or_b32_e32 v88, 32, v145
	v_mad_i64_i32 v[88:89], s[18:19], s20, v88, 0
	v_lshl_add_u64 v[96:97], v[88:89], 1, v[140:141]
	v_mul_f32_e32 v88, v100, v144
	v_mul_f32_e32 v89, v101, v144
	v_mul_f32_e32 v90, v102, v144
	v_mul_f32_e32 v91, v103, v144
	v_cvt_pk_bf16_f32 v88, v88, v89
	v_mul_f32_e32 v94, v94, v144
	v_mul_f32_e32 v95, v95, v144
	v_cvt_pk_bf16_f32 v89, v90, v91
	v_cvt_pk_bf16_f32 v90, v92, v93
	v_cvt_pk_bf16_f32 v91, v94, v95
	flat_store_dwordx4 v[96:97], v[88:91] sc1
	v_mul_f32_e32 v80, v80, v144
	v_mul_f32_e32 v81, v81, v144
	v_mul_f32_e32 v88, v72, v144
	v_mul_f32_e32 v75, v75, v144
	v_cvt_pk_bf16_f32 v72, v80, v81
	v_mul_f32_e32 v82, v82, v144
	v_mul_f32_e32 v83, v83, v144
	v_mul_f32_e32 v89, v73, v144
	v_mul_f32_e32 v90, v74, v144
	v_cvt_pk_bf16_f32 v73, v82, v83
	v_cvt_pk_bf16_f32 v74, v88, v89
	v_cvt_pk_bf16_f32 v75, v90, v75
	flat_store_dwordx4 v[96:97], v[72:75] offset:256 sc1
	v_mul_f32_e32 v76, v76, v144
	v_mul_f32_e32 v77, v77, v144
	v_or_b32_e32 v72, 48, v145
	v_mad_i64_i32 v[72:73], s[18:19], s20, v72, 0
	v_lshl_add_u64 v[80:81], v[72:73], 1, v[140:141]
	v_mul_f32_e32 v72, v84, v144
	v_mul_f32_e32 v73, v85, v144
	v_mul_f32_e32 v74, v86, v144
	v_mul_f32_e32 v75, v87, v144
	v_cvt_pk_bf16_f32 v72, v72, v73
	v_mul_f32_e32 v78, v78, v144
	v_mul_f32_e32 v79, v79, v144
	v_cvt_pk_bf16_f32 v73, v74, v75
	v_cvt_pk_bf16_f32 v74, v76, v77
	v_cvt_pk_bf16_f32 v75, v78, v79
	flat_store_dwordx4 v[80:81], v[72:75] sc1
	v_mul_f32_e32 v68, v68, v144
	v_mul_f32_e32 v69, v69, v144
	v_mul_f32_e32 v72, v64, v144
	v_mul_f32_e32 v67, v67, v144
	v_cvt_pk_bf16_f32 v64, v68, v69
	v_mul_f32_e32 v70, v70, v144
	v_mul_f32_e32 v71, v71, v144
	v_mul_f32_e32 v73, v65, v144
	v_mul_f32_e32 v74, v66, v144
	v_cvt_pk_bf16_f32 v65, v70, v71
	v_cvt_pk_bf16_f32 v66, v72, v73
; __device__ __forceinline__ float bf_lo(unsigned w) { return __uint_as_float(w << 16); }
;     __device__ __forceinline__ void operator()(const f32x4 (&acc)[2][2][4][2], const pg8::Unit& u, int wr, int wc, int fr_, int fq_) const {
;     ...
;             const int row0 = u.pm * 256 + wr * 64 + fr, col0 = colt + wc * 32 + 8 * fq;
; #pragma unroll
;             for (int ai = 0; ai < 2; ++ai)
; #pragma unroll
;                 for (int m = 0; m < 4; ++m) { const size_t roff = (size_t)(row0 + ai * 128 + m * 16) * ld + col0;
; #pragma unroll
;                     for (int bj = 0; bj < 2; ++bj) { f32x4 v0 = acc[ai][bj][m][0], v1 = acc[ai][bj][m][1]; const size_t off = roff + bj * 128;
;                         float v[8] = {v0[0], v0[1], v0[2], v0[3], v1[0], v1[1], v1[2], v1[3]};
;                         if constexpr (MODE == EPI_INPROJ) {
; #pragma unroll
;                             for (int i = 0; i < 8; ++i) v[i] *= sc;
;                         }
;                         if constexpr (MODE == EPI_GLU) {
;                             const u32x4 yg = *(const u32x4*)(X1 + off); const u32x4 zs = *(const u32x4*)(base + off);
; #pragma unroll
;                             for (int i = 0; i < 4; ++i) { v[2 * i] = bf_lo(yg[i]) * sigm(v[2 * i] * sc_all) * silu(bf_lo(zs[i])); v[2 * i + 1] = bf_hi(yg[i]) * sigm(v[2 * i + 1] * sc_all) * silu(bf_hi(zs[i])); }
;                         }
;                         if constexpr (MODE == EPI_MRG_A) {
;                             const u32x4 ga = *(const u32x4*)(base + off);
; #pragma unroll
;                             for (int i = 0; i < 4; ++i) { v[2 * i] *= sigm(bf_lo(ga[i])); v[2 * i + 1] *= sigm(bf_hi(ga[i])); }
;                         }
;                         if constexpr (MODE == EPI_MRG_B) {
;                             const u32x4 ga = *(const u32x4*)(base + off); const u32x4 gs = *(const u32x4*)(X1 + off);
; #pragma unroll
;                             for (int i = 0; i < 4; ++i) { v[2 * i] = bf_lo(ga[i]) + sigm(bf_lo(gs[i])) * v[2 * i]; v[2 * i + 1] = bf_hi(ga[i]) + sigm(bf_hi(gs[i])) * v[2 * i + 1]; }
;                         }
;                         if constexpr (MODE == EPI_OUT_A) {
;                             const f32x4 r0 = *(const f32x4*)(res + off), r1 = *(const f32x4*)(res + off + 4); const u32x4 pl = *(const u32x4*)(X1 + off);
;                             f32x4 o0, o1;
	v_cvt_pk_bf16_f32 v67, v74, v67
	flat_store_dwordx4 v[80:81], v[64:67] offset:256 sc1
	v_mul_f32_e32 v60, v60, v144
	v_mul_f32_e32 v61, v61, v144
	v_add_u32_e32 v64, 0x80, v145
	v_mad_i64_i32 v[64:65], s[18:19], s20, v64, 0
	v_lshl_add_u64 v[64:65], v[64:65], 1, v[140:141]
	v_mul_f32_e32 v66, v56, v144
	v_mul_f32_e32 v59, v59, v144
	v_cvt_pk_bf16_f32 v56, v60, v61
	v_mul_f32_e32 v62, v62, v144
	v_mul_f32_e32 v63, v63, v144
	v_mul_f32_e32 v67, v57, v144
	v_mul_f32_e32 v68, v58, v144
	v_cvt_pk_bf16_f32 v57, v62, v63
	v_cvt_pk_bf16_f32 v58, v66, v67
	v_cvt_pk_bf16_f32 v59, v68, v59
	flat_store_dwordx4 v[64:65], v[56:59] sc1
	v_mul_f32_e32 v48, v48, v144
	v_mul_f32_e32 v49, v49, v144
	v_mul_f32_e32 v56, v40, v144
	v_mul_f32_e32 v43, v43, v144
	v_cvt_pk_bf16_f32 v40, v48, v49
	v_mul_f32_e32 v50, v50, v144
	v_mul_f32_e32 v51, v51, v144
	v_mul_f32_e32 v57, v41, v144
	v_mul_f32_e32 v58, v42, v144
	v_cvt_pk_bf16_f32 v41, v50, v51
	v_cvt_pk_bf16_f32 v42, v56, v57
	v_cvt_pk_bf16_f32 v43, v58, v43
	flat_store_dwordx4 v[64:65], v[40:43] offset:256 sc1
	v_mul_f32_e32 v44, v44, v144
	v_mul_f32_e32 v45, v45, v144
	v_add_u32_e32 v40, 0x90, v145
	v_mad_i64_i32 v[40:41], s[18:19], s20, v40, 0
	v_lshl_add_u64 v[48:49], v[40:41], 1, v[140:141]
	v_mul_f32_e32 v40, v52, v144
	v_mul_f32_e32 v41, v53, v144
	v_mul_f32_e32 v42, v54, v144
	v_mul_f32_e32 v43, v55, v144
	v_cvt_pk_bf16_f32 v40, v40, v41
	v_mul_f32_e32 v46, v46, v144
	v_mul_f32_e32 v47, v47, v144
	v_cvt_pk_bf16_f32 v41, v42, v43
	v_cvt_pk_bf16_f32 v42, v44, v45
	v_cvt_pk_bf16_f32 v43, v46, v47
	flat_store_dwordx4 v[48:49], v[40:43] sc1
	v_mul_f32_e32 v32, v32, v144
	v_mul_f32_e32 v33, v33, v144
	v_mul_f32_e32 v40, v24, v144
	v_mul_f32_e32 v27, v27, v144
	v_cvt_pk_bf16_f32 v24, v32, v33
	v_mul_f32_e32 v34, v34, v144
	v_mul_f32_e32 v35, v35, v144
	v_mul_f32_e32 v41, v25, v144
	v_mul_f32_e32 v42, v26, v144
	v_cvt_pk_bf16_f32 v25, v34, v35
	v_cvt_pk_bf16_f32 v26, v40, v41
	v_cvt_pk_bf16_f32 v27, v42, v27
	flat_store_dwordx4 v[48:49], v[24:27] offset:256 sc1
	v_mul_f32_e32 v28, v28, v144
	v_mul_f32_e32 v29, v29, v144
	v_add_u32_e32 v24, 0xa0, v145
	v_mad_i64_i32 v[24:25], s[18:19], s20, v24, 0
	v_lshl_add_u64 v[32:33], v[24:25], 1, v[140:141]
	v_mul_f32_e32 v24, v36, v144
	v_mul_f32_e32 v25, v37, v144
	v_mul_f32_e32 v26, v38, v144
	v_mul_f32_e32 v27, v39, v144
	v_cvt_pk_bf16_f32 v24, v24, v25
	v_mul_f32_e32 v30, v30, v144
	v_mul_f32_e32 v31, v31, v144
	v_cvt_pk_bf16_f32 v25, v26, v27
	v_cvt_pk_bf16_f32 v26, v28, v29
	v_cvt_pk_bf16_f32 v27, v30, v31
	flat_store_dwordx4 v[32:33], v[24:27] sc1
	v_mul_f32_e32 v16, v16, v144
	v_mul_f32_e32 v17, v17, v144
	v_mul_f32_e32 v24, v8, v144
	v_mul_f32_e32 v11, v11, v144
	v_cvt_pk_bf16_f32 v8, v16, v17
	v_mul_f32_e32 v18, v18, v144
	v_mul_f32_e32 v19, v19, v144
	v_mul_f32_e32 v25, v9, v144
	v_mul_f32_e32 v26, v10, v144
	v_cvt_pk_bf16_f32 v9, v18, v19
	v_cvt_pk_bf16_f32 v10, v24, v25
	v_cvt_pk_bf16_f32 v11, v26, v11
	flat_store_dwordx4 v[32:33], v[8:11] offset:256 sc1
	v_mul_f32_e32 v12, v12, v144
	v_mul_f32_e32 v13, v13, v144
	v_add_u32_e32 v8, 0xb0, v145
	v_mad_i64_i32 v[8:9], s[18:19], s20, v8, 0
	v_lshl_add_u64 v[16:17], v[8:9], 1, v[140:141]
	v_mul_f32_e32 v8, v20, v144
	v_mul_f32_e32 v9, v21, v144
	v_mul_f32_e32 v10, v22, v144
	v_mul_f32_e32 v11, v23, v144
	v_cvt_pk_bf16_f32 v8, v8, v9
	v_cvt_pk_bf16_f32 v9, v10, v11
	v_cvt_pk_bf16_f32 v10, v12, v13
	v_mul_f32_e32 v3, v3, v144
	s_andn2_b64 vcc, exec, s[36:37]
	s_mov_b64 s[18:19], -1
	v_mul_f32_e32 v14, v14, v144
	v_mul_f32_e32 v15, v15, v144
	v_cvt_pk_bf16_f32 v11, v14, v15
	flat_store_dwordx4 v[16:17], v[8:11] sc1
	v_mul_f32_e32 v4, v4, v144
	v_mul_f32_e32 v5, v5, v144
	v_mul_f32_e32 v6, v6, v144
	v_mul_f32_e32 v7, v7, v144
	v_mul_f32_e32 v8, v0, v144
	v_mul_f32_e32 v9, v1, v144
	v_mul_f32_e32 v10, v2, v144
	v_cvt_pk_bf16_f32 v0, v4, v5
	v_cvt_pk_bf16_f32 v1, v6, v7
	v_cvt_pk_bf16_f32 v2, v8, v9
	v_cvt_pk_bf16_f32 v3, v10, v3
	flat_store_dwordx4 v[16:17], v[0:3] offset:256 sc1
	s_cbranch_vccnz .LBB0_149
	s_andn2_b64 vcc, exec, s[6:7]
	s_cbranch_vccnz .LBB0_148
	s_barrier
	s_branch .LBB0_148
